# FFN_IN tile walk regrouped 4 row panels at a time (WGM=4): 4x8 tile block per XCD round, half the L2-miss operand traffic
# speedup vs baseline: 1.0087x; 1.0070x over previous
; DI int obid() { int b = blockIdx.x; asm volatile("" : "+s"(b)); return b; }
; #define STAGE(bufoff, GB) do { const char* g_ = (GB); \
;         _Pragma("unroll") for (int i_ = 0; i_ < 2; ++i_) __builtin_amdgcn_global_load_lds((const unsigned*)(g_ + voff[i_]), (LAS3 unsigned*)(L + (bufoff) + stoff + i_ * 8192), 16, 0, 0); } while (0)
; #define VOFF_INIT() do { _Pragma("unroll") for (int i = 0; i < 2; ++i) { int R, C; stage_rc((wid * 64 + olane()) * 16 + i * 8192, R, C); voff[i] = (unsigned)(R * K + C) * 2u; } } while (0)
; template <int EPI>
; DI void gemm_phase(const bf16_t* __restrict__ A, const bf16_t* __restrict__ Bt, const int K, const int N, const Params& p, const int layer_j, char* lds) {
;     ...
;     if (obid() >= nwg) return;
;     int pm, pn;
;     TILE_COORDS(obid(), pm, pn);
;     const size_t kstep = 128, hstep = (size_t)HALF * K * 2, tstep = 2 * hstep;
;     const char* cA = (const char*)A + (size_t)pm * tstep; const char* cB = (const char*)Bt + (size_t)pn * tstep;
;     f32x4 acc[2][2][4][2];
; #pragma unroll
;     for (int a = 0; a < 2; ++a)
; #pragma unroll
;         for (int b = 0; b < 2; ++b)
; #pragma unroll
;             for (int m = 0; m < 4; ++m)
; #pragma unroll
;                 for (int n = 0; n < 2; ++n) acc[a][b][m][n] = (f32x4){0.f, 0.f, 0.f, 0.f};
;     bf16x8 At[4][2], B0[2][2], B1[2][2];
;     {
;         unsigned voff[2]; VOFF_INIT();
;         asm volatile("s_waitcnt vmcnt(0) lgkmcnt(0)" ::: "memory");
;         __syncthreads();
;         STAGE(SB(0, 0), cB); STAGE(SB(0, 1), cB + hstep); STAGE(SA(0, 0), cA); STAGE(SA(0, 1), cA + hstep);
.LBB0_34:
	s_waitcnt vmcnt(0)
	v_mbcnt_lo_u32_b32 v0, -1, 0
	v_mbcnt_hi_u32_b32 v0, -1, v0
	v_readlane_b32 s4, v254, 7
	v_and_b32_e32 v1, 15, v0
	v_and_b32_e32 v4, 48, v0
	v_or_b32_e32 v2, s4, v1
	v_lshlrev_b32_e32 v3, 6, v2
	s_movk_i32 s4, 0x3c0
	v_lshlrev_b32_e32 v5, 4, v0
	v_and_or_b32 v3, v3, s4, v4
	v_and_b32_e32 v5, 0xfffffc00, v5
	v_readlane_b32 s4, v254, 8
	v_lshlrev_b32_e32 v2, 2, v2
	v_add_lshl_u32 v136, v0, s71, 4
	v_add_u32_e32 v6, s4, v5
	v_and_b32_e32 v2, 32, v2
	v_readlane_b32 s4, v254, 9
	v_lshlrev_b32_e32 v0, 2, v0
	s_add_u32 s13, s68, 0x2481000
	v_bitop3_b32 v137, v3, v6, v2 bitop3:0xde
	v_lshl_or_b32 v1, v1, 6, v4
	v_add_u32_e32 v2, s4, v5
	v_and_b32_e32 v0, 32, v0
	s_addc_u32 s38, s69, 0
	v_bitop3_b32 v138, v1, v2, v0 bitop3:0xde
	s_mov_b32 s4, s2
	s_cmpk_gt_i32 s4, 0x57f
	s_cbranch_scc1 .LBB0_50
	v_writelane_b32 v255, s34, 12
	v_add_u32_e32 v139, 0x10000, v136
	v_add_u32_e32 v140, 0x12000, v136
	v_writelane_b32 v255, s35, 13
	v_writelane_b32 v255, s31, 14
	v_add_u32_e32 v141, 0x14000, v136
	v_readlane_b32 s4, v255, 6
	s_mul_i32 s17, s4, 0xb00000
	v_readlane_b32 s5, v255, 7
	s_mul_hi_u32 s16, s4, 0xb00000
	s_add_u32 s64, s13, s17
	s_mov_b32 s4, s2
	s_addc_u32 s65, s38, s16
	s_ashr_i32 s5, s4, 31
	s_lshr_b32 s5, s5, 29
	s_add_i32 s5, s4, s5
	s_ashr_i32 s6, s5, 3
	s_and_b32 s5, s5, -8
	s_sub_i32 s4, s4, s5
	s_cmp_lt_i32 s4, 0
	s_movk_i32 s5, 0xb1
	s_cselect_b32 s5, s5, 0xb0
	s_mul_i32 s4, s5, s4
	s_add_i32 s4, s4, s6
	s_mul_hi_i32 s5, s4, 0x2e8ba2e9
	s_lshr_b32 s6, s5, 31
	s_ashr_i32 s5, s5, 2
	s_add_i32 s5, s5, s6
	s_sub_i32 s6, 64, s5
	s_min_i32 s6, s6, 1
	s_abs_i32 s7, s6
	v_cvt_f32_u32_e32 v0, s7
	v_writelane_b32 v255, s13, 15
	s_sub_i32 s12, 0, s7
	s_mul_i32 s8, s5, 22
	v_rcp_iflag_f32_e32 v0, v0
	s_sub_i32 s4, s4, s8
	s_abs_i32 s9, s4
	s_xor_b32 s8, s4, s6
	v_mul_f32_e32 v0, 0x4f7ffffe, v0
	v_cvt_u32_f32_e32 v0, v0
	s_ashr_i32 s8, s8, 31
	v_add_u32_e32 v142, 0x16000, v136
	v_add_u32_e32 v143, 0x2000, v136
	v_readfirstlane_b32 s13, v0
	s_mul_i32 s12, s12, s13
	s_mul_hi_u32 s12, s13, s12
	s_add_i32 s13, s13, s12
	s_mul_hi_u32 s12, s9, s13
	s_mul_i32 s13, s12, s7
	s_sub_i32 s9, s9, s13
	s_add_i32 s13, s12, 1
	s_sub_i32 s18, s9, s7
	s_cmp_ge_u32 s9, s7
	s_cselect_b32 s12, s13, s12
	s_cselect_b32 s9, s18, s9
	s_add_i32 s13, s12, 1
	s_cmp_ge_u32 s9, s7
	s_cselect_b32 s7, s13, s12
	v_mbcnt_lo_u32_b32 v0, -1, 0
	v_mbcnt_hi_u32_b32 v0, -1, v0
	s_xor_b32 s7, s7, s8
	v_add_u32_e32 v1, s71, v0
	v_lshlrev_b32_e32 v2, 4, v1
	v_ashrrev_i32_e32 v1, 6, v1
	s_sub_i32 s24, s7, s8
	v_lshrrev_b32_e32 v4, 31, v1
	s_mul_i32 s6, s24, s6
	v_add_u32_e32 v4, v1, v4
	s_sub_i32 s4, s4, s6
	v_and_b32_e32 v3, 32, v0
	v_and_b32_e32 v5, 0x3fffffe, v4
	s_add_i32 s26, s5, s4
	s_and_b32 s5, s26, 3
	s_mul_i32 s5, s5, 22
	s_add_i32 s5, s5, s24
	s_and_b32 s26, s26, -4
	s_and_b32 s6, s5, 3
	s_add_i32 s26, s26, s6
	s_lshr_b32 s24, s5, 2
	v_sub_u32_e32 v1, v1, v5
	v_bitop3_b32 v2, v2, v3, 48 bitop3:0x6c
	v_lshlrev_b32_e32 v3, 14, v4
	v_lshlrev_b32_e32 v0, 9, v0
	s_movk_i32 s4, 0x7800
	v_lshlrev_b32_e32 v1, 6, v1
	v_and_b32_e32 v3, 0xffff8000, v3
	v_and_or_b32 v0, v0, s4, v2
	v_add3_u32 v32, v1, v3, v0
	v_mbcnt_lo_u32_b32 v0, -1, 0
	v_mbcnt_hi_u32_b32 v0, -1, v0
	s_ashr_i32 s27, s26, 31
	v_add_lshl_u32 v1, v0, s71, 4
	v_add_u32_e32 v2, 0x2000, v1
	s_ashr_i32 s25, s24, 31
	v_ashrrev_i32_e32 v2, 10, v2
	s_lshl_b64 s[28:29], s[26:27], 19
	s_lshl_b64 s[30:31], s[24:25], 19
	v_and_b32_e32 v3, 32, v0
	v_lshrrev_b32_e32 v4, 31, v2
	s_add_u32 s8, s82, s28
	v_add_u32_e32 v4, v2, v4
	v_bitop3_b32 v1, v1, v3, 48 bitop3:0x6c
	v_lshlrev_b32_e32 v0, 9, v0
	s_addc_u32 s9, s83, s29
	v_lshlrev_b32_e32 v3, 14, v4
	v_and_or_b32 v0, v0, s4, v1
	s_movk_i32 s4, 0x8000
	v_and_b32_e32 v5, 0x3fffffe, v4
	v_and_or_b32 v0, v3, s4, v0
	s_add_u32 s12, s64, s30
	v_readfirstlane_b32 s4, v139
	v_sub_u32_e32 v2, v2, v5
	s_addc_u32 s13, s65, s31
	s_mov_b32 m0, s4
	v_readfirstlane_b32 s4, v140
	v_lshl_add_u32 v0, v2, 6, v0
	s_waitcnt vmcnt(0) lgkmcnt(0)
	s_waitcnt lgkmcnt(0)
	s_barrier
	global_load_lds_dwordx4 v32, s[12:13]
	s_mov_b32 m0, s4
	s_add_u32 s4, s12, 0x40000
	v_readfirstlane_b32 s6, v141
	global_load_lds_dwordx4 v0, s[12:13]
	s_addc_u32 s5, s13, 0
	s_mov_b32 m0, s6
	v_readfirstlane_b32 s6, v142
	global_load_lds_dwordx4 v32, s[4:5]
	s_mov_b32 m0, s6
	v_add_u32_e32 v144, 0x4000, v136
	global_load_lds_dwordx4 v0, s[4:5]
	v_readfirstlane_b32 s4, v136
	s_mov_b32 m0, s4
	v_readfirstlane_b32 s4, v143
	global_load_lds_dwordx4 v32, s[8:9]
	s_mov_b32 m0, s4
	s_add_u32 s4, s8, 0x40000
	v_readfirstlane_b32 s6, v144
	v_add_u32_e32 v145, 0x6000, v136
	global_load_lds_dwordx4 v0, s[8:9]
	s_addc_u32 s5, s9, 0
	s_mov_b32 m0, s6
	v_readfirstlane_b32 s6, v145
	global_load_lds_dwordx4 v32, s[4:5]
	s_mov_b32 m0, s6
	v_readlane_b32 s6, v254, 10
	global_load_lds_dwordx4 v0, s[4:5]
	v_readlane_b32 s7, v254, 11
	s_mov_b32 s11, s38
	s_andn2_b64 vcc, exec, s[6:7]
	v_cndmask_b32_e64 v1, 0, 1, s[6:7]
	v_cmp_ne_u32_e64 s[4:5], 1, v1
	s_cbranch_vccnz .LBB0_37
	s_barrier

; DI int obid() { int b = blockIdx.x; asm volatile("" : "+s"(b)); return b; }
; DI int ogrid() { int g = gridDim.x; asm volatile("" : "+s"(g)); return g; }
; template <int EPI>
; DI void gemm_phase(const bf16_t* __restrict__ A, const bf16_t* __restrict__ Bt, const int K, const int N, const Params& p, const int layer_j, char* lds) {
;     ...
;         const int Lnext = (ui + 1) * ogrid() + obid();
;         const bool has_next = Lnext < nwg;
;         int pm2 = pm, pn2 = pn;
;         if (has_next) TILE_COORDS(Lnext, pm2, pn2);
.LBB0_40:
	s_mov_b32 s6, s70
	s_add_i32 s87, s87, 1
	s_mul_i32 s13, s6, s87
	s_mov_b32 s6, s2
	s_add_i32 s13, s13, s6
	s_cmpk_lt_i32 s13, 0x580
	s_cselect_b64 s[18:19], -1, 0
	s_cmpk_gt_i32 s13, 0x57f
	s_mov_b32 s16, s24
	s_mov_b32 s12, s26
	s_cbranch_scc1 .LBB0_42
	s_ashr_i32 s6, s13, 31
	s_lshr_b32 s6, s6, 29
	s_add_i32 s6, s13, s6
	s_ashr_i32 s7, s6, 3
	s_and_b32 s6, s6, -8
	s_sub_i32 s6, s13, s6
	s_cmp_lt_i32 s6, 0
	s_movk_i32 s10, 0xb1
	s_cselect_b32 s12, s10, 0xb0
	s_mul_i32 s6, s12, s6
	s_add_i32 s6, s6, s7
	s_mul_hi_i32 s7, s6, 0x2e8ba2e9
	s_lshr_b32 s12, s7, 31
	s_ashr_i32 s7, s7, 2
	s_add_i32 s12, s7, s12
	s_mul_i32 s7, s12, 22
	s_sub_i32 s16, s6, s7
	s_and_b32 s6, s12, 3
	s_mul_i32 s6, s6, 22
	s_add_i32 s6, s6, s16
	s_and_b32 s12, s12, -4
	s_and_b32 s7, s6, 3
	s_add_i32 s12, s12, s7
	s_lshr_b32 s16, s6, 2
